# pool_prep: rotate the channel-group index per iteration so every wave does one item of each window width (balances per-wave work)
# speedup vs baseline: 1.0081x; 1.0050x over previous
.LBB0_153:
	s_bitcmp1_b32 s4, 0
	s_cselect_b64 s[0:1], -1, 0
	v_writelane_b32 v254, s4, 58
	s_lshr_b32 s4, s4, 1
	v_writelane_b32 v254, s4, 59
	s_cmp_le_i32 s68, s80
	s_nop 0
	v_writelane_b32 v254, s5, 60
	s_cselect_b64 s[4:5], -1, 0
	s_cmp_lt_i32 s80, s69
	s_waitcnt lgkmcnt(0)
	s_cselect_b64 s[6:7], -1, 0
	s_and_b64 vcc, exec, s[0:1]
	s_and_b64 s[0:1], s[4:5], s[6:7]
	s_waitcnt vmcnt(0)
	v_cndmask_b32_e64 v0, 0, 1, s[0:1]
	s_mov_b64 s[0:1], 0
	v_writelane_b32 v254, s0, 61
	v_cmp_ne_u32_e64 s[64:65], 1, v0
	s_nop 0
	v_writelane_b32 v254, s1, 62
	s_mov_b64 s[0:1], -1
	s_cbranch_vccz .LBB0_766
	s_and_b64 vcc, exec, s[64:65]
	s_cbranch_vccnz .LBB0_657
	s_mov_b32 s1, s2
	s_mov_b32 s0, s73
	s_lshl_b32 s1, s1, 3
	v_readlane_b32 s4, v254, 4
	s_add_i32 s6, s1, s4
	s_mov_b64 s[48:49], s[66:67]
	s_cmpk_gt_i32 s6, 0x203f
	v_readlane_b32 s5, v254, 5
	v_mbcnt_lo_u32_b32 v0, -1, 0
	v_mbcnt_hi_u32_b32 v0, -1, v0
	s_cbranch_scc1 .LBB0_611
	s_load_dwordx8 s[40:47], s[48:49], 0xb0
	v_readlane_b32 s1, v254, 58
	s_add_i32 s1, s1, -1
	s_mul_i32 s92, s1, 0x40800
	s_lshl_b64 s[4:5], s[92:93], 2
	s_waitcnt lgkmcnt(0)
	s_add_u32 s4, s46, s4
	s_addc_u32 s5, s47, s5
	s_add_u32 s50, s4, 0x181000
	s_addc_u32 s51, s5, 0
	s_lshl_b32 s92, s1, 10
	s_lshl_b32 s7, s0, 3
	s_lshl_b64 s[0:1], s[92:93], 2
	s_add_u32 s4, s42, s0
	s_addc_u32 s5, s43, s1
	s_add_u32 s0, s40, s0
	v_readlane_b32 s8, v254, 59
	v_ashrrev_i32_e32 v153, 5, v0
	v_lshlrev_b32_e32 v0, 3, v0
	s_addc_u32 s1, s41, s1
	s_lshl_b32 s92, s8, 5
	v_and_b32_e32 v0, 0xf8, v0
	v_readlane_b32 s8, v254, 7
	v_mov_b32_e32 v1, v161
	v_readlane_b32 s9, v254, 60
	v_or_b32_e32 v152, s8, v0
	v_lshlrev_b32_e32 v160, 2, v152
	v_lshlrev_b32_e32 v0, 1, v152
	v_lshl_add_u64 v[154:155], s[0:1], 0, v[160:161]
	v_lshl_add_u64 v[0:1], s[46:47], 0, v[0:1]
	s_mov_b64 s[0:1], 0x15f10000
	v_lshl_add_u64 v[158:159], v[0:1], 0, s[0:1]
	s_mov_b64 s[0:1], 0x1e010000
	v_lshl_add_u64 v[162:163], v[0:1], 0, s[0:1]
	v_lshl_add_u64 v[0:1], s[44:45], 0, v[160:161]
	s_mov_b64 s[0:1], 0x31200000
	v_lshl_add_u64 v[164:165], v[0:1], 0, s[0:1]
	s_mov_b64 s[0:1], 0x32c80000
	v_lshl_add_u64 v[156:157], s[4:5], 0, v[160:161]
	v_lshl_add_u64 v[166:167], v[0:1], 0, s[0:1]
	s_mov_b32 s58, s77
	s_branch .LBB0_158
.LBB0_157:
	s_or_b64 exec, exec, s[0:1]
	s_add_i32 s6, s6, s7
	s_cmpk_lt_i32 s6, 0x2040
	s_cbranch_scc0 .LBB0_611
	s_add_i32 s58, s58, 1
	s_and_b32 s58, s58, 3
	s_cmp_eq_u32 s58, 0
	s_cselect_b32 s59, 1, 0
	s_lshl_b32 s60, s59, 12
	s_sub_i32 s60, 0x400, s60
	s_ashr_i32 s61, s60, 31
	s_ashr_i32 s62, s60, 1
	s_ashr_i32 s63, s62, 31
	s_ashr_i32 s59, s60, 2
	v_add_u32_e32 v152, s59, v152
	v_lshl_add_u64 v[154:155], v[154:155], 0, s[60:61]
	v_lshl_add_u64 v[156:157], v[156:157], 0, s[60:61]
	v_lshl_add_u64 v[164:165], v[164:165], 0, s[60:61]
	v_lshl_add_u64 v[166:167], v[166:167], 0, s[60:61]
	v_lshl_add_u64 v[158:159], v[158:159], 0, s[62:63]
	v_lshl_add_u64 v[162:163], v[162:163], 0, s[62:63]
.LBB0_158:
	global_load_dwordx4 v[0:3], v[154:155], off offset:16
	global_load_dwordx4 v[8:11], v[154:155], off
	global_load_dwordx4 v[4:7], v[156:157], off offset:16
	global_load_dwordx4 v[12:15], v[156:157], off
	s_ashr_i32 s0, s6, 1
	s_and_b32 s0, s0, -2
	v_add_u32_e32 v196, s0, v153
	s_movk_i32 s0, 0xfff
	v_lshlrev_b32_e32 v168, 4, v196
	v_cmp_lt_i32_e64 s[40:41], s0, v196
	s_cmp_lt_i32 s58, 2
	v_cmp_gt_i32_e64 s[42:43], s72, v196
	s_cbranch_scc1 .LBB0_248
	s_cmp_gt_i32 s58, 2
	s_cbranch_scc0 .LBB0_249
	s_and_saveexec_b64 s[0:1], s[42:43]
	s_xor_b64 s[0:1], exec, s[0:1]
	v_ashrrev_i32_e32 v16, 31, v196
	v_lshrrev_b32_e32 v16, 25, v16
	v_add_u32_e32 v16, v196, v16
	v_ashrrev_i32_e32 v16, 7, v16
	s_andn2_saveexec_b64 s[0:1], s[0:1]
	v_add_u32_e32 v16, 0xffff0000, v168
	v_lshrrev_b32_e32 v16, 4, v16
	s_or_b64 exec, exec, s[0:1]
	v_ashrrev_i32_e32 v169, 31, v168
	v_lshrrev_b32_e32 v17, 21, v169
	v_add_u32_e32 v17, v168, v17
	v_and_b32_e32 v17, 0xfffff800, v17
	v_sub_u32_e32 v197, v168, v17
	v_cndmask_b32_e64 v198, v197, 0, s[40:41]
	v_cmp_gt_i32_e64 s[44:45], 16, v198
	v_cmp_lt_i32_e32 vcc, 15, v198
	v_mov_b32_e32 v172, 0
	v_mov_b32_e32 v173, 0
	v_mov_b32_e32 v174, 0
	v_mov_b32_e32 v175, 0
	v_mov_b32_e32 v178, 0
	v_mov_b32_e32 v179, 0
	v_mov_b32_e32 v176, 0
	v_mov_b32_e32 v177, 0
	s_and_saveexec_b64 s[0:1], vcc
	s_cbranch_execz .LBB0_166
	v_add_u32_e32 v18, -16, v168
	v_ashrrev_i32_e32 v19, 31, v18
	v_lshlrev_b64 v[20:21], 11, v[18:19]
	v_lshl_add_u64 v[20:21], v[158:159], 0, v[20:21]
	v_lshl_add_u64 v[18:19], v[18:19], 3, s[50:51]
	global_load_dwordx2 v[22:23], v[18:19], off
	s_nop 0
	global_load_dwordx4 v[18:21], v[20:21], off
	s_waitcnt vmcnt(0)
	v_pk_mul_f32 v[22:23], v[22:23], s[96:97] op_sel_hi:[1,0]
	v_lshlrev_b32_e32 v17, 16, v18
	v_fma_f32 v23, -v22, v22, v23
	v_lshlrev_b32_e32 v26, 16, v20
	v_and_b32_e32 v27, 0xffff0000, v20
	v_sub_f32_e32 v20, v17, v22
	v_max_f32_e32 v17, 0, v23
	v_add_f32_e32 v17, 0x3727c5ac, v17
	v_mul_f32_e32 v23, 0x4f800000, v17
	v_cmp_gt_f32_e32 vcc, s97, v17
	v_and_b32_e32 v24, 0xffff0000, v18
	v_lshlrev_b32_e32 v28, 16, v21
	v_cndmask_b32_e32 v17, v17, v23, vcc
	v_sqrt_f32_e32 v29, v17
	v_sub_f32_e32 v23, v27, v22
	v_and_b32_e32 v25, 0xffff0000, v21
	v_sub_f32_e32 v21, v24, v22
	v_add_u32_e32 v27, -1, v29
	v_sub_f32_e32 v24, v28, v22
	v_add_u32_e32 v28, 1, v29
	v_fma_f32 v30, -v27, v29, v17
	v_fma_f32 v31, -v28, v29, v17
	v_cmp_ge_f32_e64 s[46:47], 0, v30
	v_lshlrev_b32_e32 v18, 16, v19
	v_and_b32_e32 v19, 0xffff0000, v19
	v_cndmask_b32_e64 v27, v29, v27, s[46:47]
	v_cmp_lt_f32_e64 s[46:47], 0, v31
	v_sub_f32_e32 v19, v19, v22
	v_sub_f32_e32 v18, v18, v22
	v_cndmask_b32_e64 v27, v27, v28, s[46:47]
	v_mul_f32_e32 v28, 0x37800000, v27
	v_cndmask_b32_e32 v27, v27, v28, vcc
	v_cmp_class_f32_e32 vcc, v17, v248
	v_sub_f32_e32 v25, v25, v22
	v_sub_f32_e32 v22, v26, v22
	v_cndmask_b32_e32 v17, v27, v17, vcc
	v_div_scale_f32 v27, s[4:5], v17, v17, 1.0
	v_rcp_f32_e32 v28, v27
	v_div_scale_f32 v26, vcc, 1.0, v17, 1.0
	v_fma_f32 v29, -v27, v28, 1.0
	v_fmac_f32_e32 v28, v29, v28
	v_mul_f32_e32 v29, v26, v28
	v_fma_f32 v30, -v27, v29, v26
	v_fmac_f32_e32 v29, v30, v28
	v_fma_f32 v26, -v27, v29, v26
	v_div_fmas_f32 v26, v26, v28, v29
	v_div_fixup_f32 v26, v26, v17, 1.0
	v_pk_mul_f32 v[20:21], v[20:21], v[26:27] op_sel_hi:[1,0]
	v_pk_mul_f32 v[18:19], v[18:19], v[26:27] op_sel_hi:[1,0]
	v_pk_mul_f32 v[22:23], v[22:23], v[26:27] op_sel_hi:[1,0]
	v_pk_mul_f32 v[24:25], v[24:25], v[26:27] op_sel_hi:[1,0]
	v_pk_fma_f32 v[176:177], v[10:11], v[18:19], v[14:15]
	v_pk_fma_f32 v[178:179], v[8:9], v[20:21], v[12:13]
	v_pk_fma_f32 v[174:175], v[2:3], v[24:25], v[6:7]
	v_pk_fma_f32 v[172:173], v[0:1], v[22:23], v[4:5]

.LBB0_437:
	s_cmp_lg_u32 s58, 1
	s_mov_b64 s[0:1], -1
	s_cbranch_scc0 .LBB0_446
	s_and_saveexec_b64 s[0:1], s[42:43]
	s_xor_b64 s[0:1], exec, s[0:1]
	v_ashrrev_i32_e32 v16, 31, v196
	v_lshrrev_b32_e32 v16, 25, v16
	v_add_u32_e32 v16, v196, v16
	v_ashrrev_i32_e32 v16, 7, v16
	s_andn2_saveexec_b64 s[0:1], s[0:1]
	v_add_u32_e32 v16, 0xffff0000, v168
	v_lshrrev_b32_e32 v16, 4, v16
	s_or_b64 exec, exec, s[0:1]
	v_ashrrev_i32_e32 v169, 31, v168
	v_lshrrev_b32_e32 v17, 21, v169
	v_add_u32_e32 v17, v168, v17
	v_and_b32_e32 v17, 0xfffff800, v17
	v_sub_u32_e32 v110, v168, v17
	v_cndmask_b32_e64 v111, v110, 0, s[40:41]
	v_ashrrev_i32_e32 v17, 31, v16
	v_cmp_gt_i32_e64 s[44:45], 2, v111
	v_lshl_add_u64 v[16:17], v[16:17], 0, s[92:93]
	v_or_b32_e32 v112, 13, v111
	s_and_saveexec_b64 s[0:1], s[44:45]
	s_xor_b64 s[0:1], exec, s[0:1]
	s_cbranch_execz .LBB0_447
	v_cmp_gt_u32_e32 vcc, 15, v112
	s_and_b64 s[8:9], s[40:41], vcc
	v_mov_b32_e32 v47, 0
	v_mov_b32_e32 v46, 0
	v_mov_b32_e32 v45, 0
	v_mov_b32_e32 v44, 0
	v_mov_b32_e32 v43, 0
	v_mov_b32_e32 v42, 0
	v_mov_b32_e32 v41, 0
	v_mov_b32_e32 v40, 0
	s_and_saveexec_b64 s[4:5], s[8:9]
	s_cbranch_execz .LBB0_445
	s_load_dwordx2 s[8:9], s[48:49], 0x28
	s_mov_b32 s18, 0xf000
	v_lshlrev_b32_e32 v160, 2, v152
	s_waitcnt lgkmcnt(0)
	v_mov_b64_e32 v[18:19], s[8:9]
	v_mad_u64_u32 v[18:19], s[8:9], v16, s18, v[18:19]
	v_mad_i32_i24 v19, v17, s18, v19
	v_lshl_add_u64 v[18:19], v[18:19], 0, v[160:161]
	s_mov_b64 s[8:9], 0xd000
	v_lshl_add_u64 v[20:21], v[18:19], 0, s[8:9]
	v_add_co_u32_e32 v18, vcc, 0xd000, v18
	s_nop 1
	v_addc_co_u32_e32 v19, vcc, 0, v19, vcc
	global_load_dwordx4 v[44:47], v[18:19], off
	global_load_dwordx4 v[40:43], v[20:21], off offset:16
